# hierarchical grid barrier: 8 per-group arrival counters (32 WGs each) + top-level counter to cut same-address atomic serialization
# baseline (speedup 1.0000x reference)
; __device__ __forceinline__ void grid_barrier(unsigned* bar, unsigned& epoch) {
;     asm volatile("s_waitcnt vmcnt(0) lgkmcnt(0)" ::: "memory");
;     __syncthreads();
;     epoch += 1;
;     if (threadIdx.x == 0) {
;         __builtin_amdgcn_fence(__ATOMIC_RELEASE, "agent");
;         asm volatile("s_waitcnt vmcnt(0)" ::: "memory");
;         const unsigned old = __hip_atomic_fetch_add(bar, 1u, __ATOMIC_RELAXED, __HIP_MEMORY_SCOPE_AGENT);
.LBB0_273:
	s_or_b64 exec, exec, s[0:1]
	s_waitcnt vmcnt(0) lgkmcnt(0)
	s_barrier
	v_cmp_eq_u32_e64 s[2:3], 0, v208
	s_mov_b64 s[0:1], exec
	s_nop 0
	v_writelane_b32 v254, s2, 32
	s_nop 1
	v_writelane_b32 v254, s3, 33
	s_and_b64 s[2:3], s[0:1], s[2:3]
	s_mov_b64 exec, s[2:3]
	s_cbranch_execz .LBB0_282
	s_mov_b64 s[2:3], exec
	buffer_wbl2 sc1
	s_waitcnt vmcnt(0)
	s_waitcnt vmcnt(0)
	v_mbcnt_lo_u32_b32 v0, s2, 0
	v_mbcnt_hi_u32_b32 v0, s3, v0
	v_cmp_eq_u32_e32 vcc, 0, v0
	s_and_saveexec_b64 s[4:5], vcc
	s_cbranch_execz .LBB0_276
	s_bcnt1_i32_b64 s2, s[2:3]
	v_mov_b32_e32 v1, 0
	v_mov_b32_e32 v2, s2
	s_cmpk_lg_u32 s45, 0x100
	s_cbranch_scc1 .Lhb_orig_0
	v_readlane_b32 vcc_lo, v253, 0
	s_and_b32 vcc_lo, vcc_lo, 7
	s_lshl_b32 vcc_lo, vcc_lo, 8
	s_addk_i32 vcc_lo, 0x1400
	v_mov_b32_e32 v0, vcc_lo
	v_mov_b32_e32 v1, 1
	global_atomic_add v1, v0, v1, s[30:31] sc0
	s_waitcnt vmcnt(0)
	v_readfirstlane_b32 vcc_lo, v1
	v_mov_b32_e32 v0, 0
	s_add_i32 vcc_lo, vcc_lo, 1
	s_and_b32 vcc_lo, vcc_lo, 31
	s_cmp_eq_u32 vcc_lo, 0
	s_cbranch_scc1 .Lhb_last_0
	v_mov_b32_e32 v1, 0x7fffff00
	s_branch .LBB0_276
.Lhb_last_0:
	v_mov_b32_e32 v1, 32
	global_atomic_add v1, v0, v1, s[30:31] sc0
	s_waitcnt vmcnt(0)
	v_add_u32_e32 v1, 31, v1
	s_branch .LBB0_276
.Lhb_orig_0:
	global_atomic_add v1, v1, v2, s[30:31] sc0

; __device__ __forceinline__ void grid_barrier(unsigned* bar, unsigned& epoch) {
;     asm volatile("s_waitcnt vmcnt(0) lgkmcnt(0)" ::: "memory");
;     __syncthreads();
;     epoch += 1;
;     if (threadIdx.x == 0) {
;         __builtin_amdgcn_fence(__ATOMIC_RELEASE, "agent");
;         asm volatile("s_waitcnt vmcnt(0)" ::: "memory");
;         const unsigned old = __hip_atomic_fetch_add(bar, 1u, __ATOMIC_RELAXED, __HIP_MEMORY_SCOPE_AGENT);
.LBB0_289:
	s_or_b64 exec, exec, s[0:1]
	s_waitcnt vmcnt(0) lgkmcnt(0)
	s_barrier
	s_mov_b64 s[0:1], exec
	v_readlane_b32 s2, v254, 32
	v_readlane_b32 s3, v254, 33
	s_and_b64 s[2:3], s[0:1], s[2:3]
	s_mov_b64 exec, s[2:3]
	s_cbranch_execz .LBB0_298
	s_mov_b64 s[2:3], exec
	buffer_wbl2 sc1
	s_waitcnt vmcnt(0)
	s_waitcnt vmcnt(0)
	v_mbcnt_lo_u32_b32 v0, s2, 0
	v_mbcnt_hi_u32_b32 v0, s3, v0
	v_cmp_eq_u32_e32 vcc, 0, v0
	s_and_saveexec_b64 s[4:5], vcc
	s_cbranch_execz .LBB0_292
	s_bcnt1_i32_b64 s2, s[2:3]
	v_mov_b32_e32 v1, 0
	v_mov_b32_e32 v2, s2
	s_cmpk_lg_u32 s45, 0x100
	s_cbranch_scc1 .Lhb_orig_1
	v_readlane_b32 vcc_lo, v253, 0
	s_and_b32 vcc_lo, vcc_lo, 7
	s_lshl_b32 vcc_lo, vcc_lo, 8
	s_addk_i32 vcc_lo, 0x1400
	v_mov_b32_e32 v0, vcc_lo
	v_mov_b32_e32 v1, 1
	global_atomic_add v1, v0, v1, s[30:31] sc0
	s_waitcnt vmcnt(0)
	v_readfirstlane_b32 vcc_lo, v1
	v_mov_b32_e32 v0, 0
	s_add_i32 vcc_lo, vcc_lo, 1
	s_and_b32 vcc_lo, vcc_lo, 31
	s_cmp_eq_u32 vcc_lo, 0
	s_cbranch_scc1 .Lhb_last_1
	v_mov_b32_e32 v1, 0x7fffff00
	s_branch .LBB0_292

; __device__ __forceinline__ void grid_barrier(unsigned* bar, unsigned& epoch) {
;     asm volatile("s_waitcnt vmcnt(0) lgkmcnt(0)" ::: "memory");
;     __syncthreads();
;     epoch += 1;
;     if (threadIdx.x == 0) {
;         __builtin_amdgcn_fence(__ATOMIC_RELEASE, "agent");
;         asm volatile("s_waitcnt vmcnt(0)" ::: "memory");
;         const unsigned old = __hip_atomic_fetch_add(bar, 1u, __ATOMIC_RELAXED, __HIP_MEMORY_SCOPE_AGENT);
.LBB0_365:
	s_waitcnt vmcnt(0) lgkmcnt(0)
	s_waitcnt vmcnt(0)
	s_barrier
	s_mov_b64 s[2:3], exec
	v_readlane_b32 s4, v254, 32
	v_readlane_b32 s5, v254, 33
	s_and_b64 s[4:5], s[2:3], s[4:5]
	s_mov_b64 exec, s[4:5]
	s_cbranch_execz .LBB0_374
	s_mov_b64 s[4:5], exec
	buffer_wbl2 sc1
	s_waitcnt vmcnt(0)
	v_mbcnt_lo_u32_b32 v0, s4, 0
	v_mbcnt_hi_u32_b32 v0, s5, v0
	v_cmp_eq_u32_e32 vcc, 0, v0
	s_and_saveexec_b64 s[6:7], vcc
	s_cbranch_execz .LBB0_368
	s_bcnt1_i32_b64 s4, s[4:5]
	v_mov_b32_e32 v1, s4
	v_readlane_b32 s4, v254, 35
	v_readlane_b32 s5, v254, 36
	s_nop 4
	s_cmpk_lg_u32 s45, 0x100
	s_cbranch_scc1 .Lhb_orig_2
	v_readlane_b32 vcc_lo, v253, 0
	s_and_b32 vcc_lo, vcc_lo, 7
	s_lshl_b32 vcc_lo, vcc_lo, 8
	s_addk_i32 vcc_lo, 0x1400
	v_mov_b32_e32 v0, vcc_lo
	v_mov_b32_e32 v1, 1
	global_atomic_add v1, v0, v1, s[4:5] sc0
	s_waitcnt vmcnt(0)
	v_readfirstlane_b32 vcc_lo, v1
	v_mov_b32_e32 v0, 0
	s_add_i32 vcc_lo, vcc_lo, 1
	s_and_b32 vcc_lo, vcc_lo, 31
	s_cmp_eq_u32 vcc_lo, 0
	s_cbranch_scc1 .Lhb_last_2
	v_mov_b32_e32 v1, 0x7fffff00
	s_branch .LBB0_368
.Lhb_last_2:
	v_mov_b32_e32 v1, 32
	global_atomic_add v1, v0, v1, s[4:5] sc0
	s_waitcnt vmcnt(0)
	v_add_u32_e32 v1, 31, v1
	s_branch .LBB0_368
.Lhb_orig_2:
	global_atomic_add v1, v161, v1, s[4:5] sc0

; __device__ __forceinline__ void grid_barrier(unsigned* bar, unsigned& epoch) {
;     asm volatile("s_waitcnt vmcnt(0) lgkmcnt(0)" ::: "memory");
;     __syncthreads();
;     epoch += 1;
;     if (threadIdx.x == 0) {
;         __builtin_amdgcn_fence(__ATOMIC_RELEASE, "agent");
;         asm volatile("s_waitcnt vmcnt(0)" ::: "memory");
;         const unsigned old = __hip_atomic_fetch_add(bar, 1u, __ATOMIC_RELAXED, __HIP_MEMORY_SCOPE_AGENT);
.LBB0_386:
	s_waitcnt vmcnt(0) lgkmcnt(0)
	s_barrier
	s_mov_b64 s[2:3], exec
	v_readlane_b32 s4, v254, 32
	v_readlane_b32 s5, v254, 33
	s_and_b64 s[4:5], s[2:3], s[4:5]
	s_mov_b64 exec, s[4:5]
	s_cbranch_execz .LBB0_395
	s_mov_b64 s[4:5], exec
	buffer_wbl2 sc1
	s_waitcnt vmcnt(0)
	s_waitcnt vmcnt(0)
	v_mbcnt_lo_u32_b32 v0, s4, 0
	v_mbcnt_hi_u32_b32 v0, s5, v0
	v_cmp_eq_u32_e32 vcc, 0, v0
	s_and_saveexec_b64 s[6:7], vcc
	s_cbranch_execz .LBB0_389
	s_bcnt1_i32_b64 s4, s[4:5]
	v_mov_b32_e32 v1, s4
	v_readlane_b32 s4, v254, 35
	v_readlane_b32 s5, v254, 36
	s_nop 4
	s_cmpk_lg_u32 s45, 0x100
	s_cbranch_scc1 .Lhb_orig_3
	v_readlane_b32 vcc_lo, v253, 0
	s_and_b32 vcc_lo, vcc_lo, 7
	s_lshl_b32 vcc_lo, vcc_lo, 8
	s_addk_i32 vcc_lo, 0x1400
	v_mov_b32_e32 v0, vcc_lo
	v_mov_b32_e32 v1, 1
	global_atomic_add v1, v0, v1, s[4:5] sc0
	s_waitcnt vmcnt(0)
	v_readfirstlane_b32 vcc_lo, v1
	v_mov_b32_e32 v0, 0
	s_add_i32 vcc_lo, vcc_lo, 1
	s_and_b32 vcc_lo, vcc_lo, 31
	s_cmp_eq_u32 vcc_lo, 0
	s_cbranch_scc1 .Lhb_last_3
	v_mov_b32_e32 v1, 0x7fffff00
	s_branch .LBB0_389

; __device__ __forceinline__ void grid_barrier(unsigned* bar, unsigned& epoch) {
;     asm volatile("s_waitcnt vmcnt(0) lgkmcnt(0)" ::: "memory");
;     __syncthreads();
;     epoch += 1;
;     if (threadIdx.x == 0) {
;         __builtin_amdgcn_fence(__ATOMIC_RELEASE, "agent");
;         asm volatile("s_waitcnt vmcnt(0)" ::: "memory");
;         const unsigned old = __hip_atomic_fetch_add(bar, 1u, __ATOMIC_RELAXED, __HIP_MEMORY_SCOPE_AGENT);
.LBB0_504:
	s_waitcnt vmcnt(0) lgkmcnt(0)
	s_waitcnt vmcnt(0) lgkmcnt(0)
	s_barrier
	s_mov_b64 s[2:3], exec
	v_readlane_b32 s4, v254, 32
	v_readlane_b32 s5, v254, 33
	s_and_b64 s[4:5], s[2:3], s[4:5]
	s_mov_b64 exec, s[4:5]
	s_cbranch_execz .LBB0_513
	s_mov_b64 s[4:5], exec
	buffer_wbl2 sc1
	s_waitcnt vmcnt(0)
	v_mbcnt_lo_u32_b32 v0, s4, 0
	v_mbcnt_hi_u32_b32 v0, s5, v0
	v_cmp_eq_u32_e32 vcc, 0, v0
	s_and_saveexec_b64 s[6:7], vcc
	s_cbranch_execz .LBB0_507
	s_bcnt1_i32_b64 s4, s[4:5]
	v_mov_b32_e32 v1, s4
	v_readlane_b32 s4, v254, 35
	v_readlane_b32 s5, v254, 36
	s_nop 4
	s_cmpk_lg_u32 s45, 0x100
	s_cbranch_scc1 .Lhb_orig_4
	v_readlane_b32 vcc_lo, v253, 0
	s_and_b32 vcc_lo, vcc_lo, 7
	s_lshl_b32 vcc_lo, vcc_lo, 8
	s_addk_i32 vcc_lo, 0x1400
	v_mov_b32_e32 v0, vcc_lo
	v_mov_b32_e32 v1, 1
	global_atomic_add v1, v0, v1, s[4:5] sc0
	s_waitcnt vmcnt(0)
	v_readfirstlane_b32 vcc_lo, v1
	v_mov_b32_e32 v0, 0
	s_add_i32 vcc_lo, vcc_lo, 1
	s_and_b32 vcc_lo, vcc_lo, 31
	s_cmp_eq_u32 vcc_lo, 0
	s_cbranch_scc1 .Lhb_last_4
	v_mov_b32_e32 v1, 0x7fffff00
	s_branch .LBB0_507

; __device__ __forceinline__ void grid_barrier(unsigned* bar, unsigned& epoch) {
;     asm volatile("s_waitcnt vmcnt(0) lgkmcnt(0)" ::: "memory");
;     __syncthreads();
;     epoch += 1;
;     if (threadIdx.x == 0) {
;         __builtin_amdgcn_fence(__ATOMIC_RELEASE, "agent");
;         asm volatile("s_waitcnt vmcnt(0)" ::: "memory");
;         const unsigned old = __hip_atomic_fetch_add(bar, 1u, __ATOMIC_RELAXED, __HIP_MEMORY_SCOPE_AGENT);
.LBB0_636:
	s_waitcnt vmcnt(0) lgkmcnt(0)
	s_barrier
	s_mov_b64 s[2:3], exec
	v_readlane_b32 s4, v254, 32
	v_readlane_b32 s5, v254, 33
	s_and_b64 s[4:5], s[2:3], s[4:5]
	s_mov_b64 s[58:59], 0x380
	s_mov_b64 s[60:61], 0x100
	s_mov_b64 s[62:63], 0x200
	s_mov_b64 s[64:65], 0x280
	s_mov_b64 exec, s[4:5]
	s_cbranch_execz .LBB0_645
	s_mov_b64 s[4:5], exec
	buffer_wbl2 sc1
	s_waitcnt vmcnt(0)
	s_waitcnt vmcnt(0)
	v_mbcnt_lo_u32_b32 v0, s4, 0
	v_mbcnt_hi_u32_b32 v0, s5, v0
	v_cmp_eq_u32_e32 vcc, 0, v0
	s_and_saveexec_b64 s[6:7], vcc
	s_cbranch_execz .LBB0_639
	s_bcnt1_i32_b64 s4, s[4:5]
	v_mov_b32_e32 v1, s4
	v_readlane_b32 s4, v254, 35
	v_readlane_b32 s5, v254, 36
	s_nop 4
	s_cmpk_lg_u32 s45, 0x100
	s_cbranch_scc1 .Lhb_orig_5
	v_readlane_b32 vcc_lo, v253, 0
	s_and_b32 vcc_lo, vcc_lo, 7
	s_lshl_b32 vcc_lo, vcc_lo, 8
	s_addk_i32 vcc_lo, 0x1400
	v_mov_b32_e32 v0, vcc_lo
	v_mov_b32_e32 v1, 1
	global_atomic_add v1, v0, v1, s[4:5] sc0
	s_waitcnt vmcnt(0)
	v_readfirstlane_b32 vcc_lo, v1
	v_mov_b32_e32 v0, 0
	s_add_i32 vcc_lo, vcc_lo, 1
	s_and_b32 vcc_lo, vcc_lo, 31
	s_cmp_eq_u32 vcc_lo, 0
	s_cbranch_scc1 .Lhb_last_5
	v_mov_b32_e32 v1, 0x7fffff00
	s_branch .LBB0_639

; __device__ __forceinline__ void grid_barrier(unsigned* bar, unsigned& epoch) {
;     asm volatile("s_waitcnt vmcnt(0) lgkmcnt(0)" ::: "memory");
;     __syncthreads();
;     epoch += 1;
;     if (threadIdx.x == 0) {
;         __builtin_amdgcn_fence(__ATOMIC_RELEASE, "agent");
;         asm volatile("s_waitcnt vmcnt(0)" ::: "memory");
;         const unsigned old = __hip_atomic_fetch_add(bar, 1u, __ATOMIC_RELAXED, __HIP_MEMORY_SCOPE_AGENT);
.LBB0_990:
	s_waitcnt vmcnt(0) lgkmcnt(0)
	s_waitcnt lgkmcnt(0)
	s_barrier
	s_mov_b64 s[2:3], exec
	v_readlane_b32 s4, v254, 32
	v_readlane_b32 s5, v254, 33
	s_and_b64 s[4:5], s[2:3], s[4:5]
	s_mov_b64 exec, s[4:5]
	s_cbranch_execz .LBB0_999
	s_mov_b64 s[4:5], exec
	buffer_wbl2 sc1
	s_waitcnt vmcnt(0)
	s_waitcnt vmcnt(0)
	v_mbcnt_lo_u32_b32 v0, s4, 0
	v_mbcnt_hi_u32_b32 v0, s5, v0
	v_cmp_eq_u32_e32 vcc, 0, v0
	s_and_saveexec_b64 s[6:7], vcc
	s_cbranch_execz .LBB0_993
	s_bcnt1_i32_b64 s4, s[4:5]
	v_mov_b32_e32 v1, s4
	v_readlane_b32 s4, v254, 35
	v_readlane_b32 s5, v254, 36
	s_nop 4
	s_cmpk_lg_u32 s45, 0x100
	s_cbranch_scc1 .Lhb_orig_8
	v_readlane_b32 vcc_lo, v253, 0
	s_and_b32 vcc_lo, vcc_lo, 7
	s_lshl_b32 vcc_lo, vcc_lo, 8
	s_addk_i32 vcc_lo, 0x1400
	v_mov_b32_e32 v0, vcc_lo
	v_mov_b32_e32 v1, 1
	global_atomic_add v1, v0, v1, s[4:5] sc0
	s_waitcnt vmcnt(0)
	v_readfirstlane_b32 vcc_lo, v1
	v_mov_b32_e32 v0, 0
	s_add_i32 vcc_lo, vcc_lo, 1
	s_and_b32 vcc_lo, vcc_lo, 31
	s_cmp_eq_u32 vcc_lo, 0
	s_cbranch_scc1 .Lhb_last_8
	v_mov_b32_e32 v1, 0x7fffff00
	s_branch .LBB0_993

; __device__ __forceinline__ void grid_barrier(unsigned* bar, unsigned& epoch) {
;     asm volatile("s_waitcnt vmcnt(0) lgkmcnt(0)" ::: "memory");
;     __syncthreads();
;     epoch += 1;
;     if (threadIdx.x == 0) {
;         __builtin_amdgcn_fence(__ATOMIC_RELEASE, "agent");
;         asm volatile("s_waitcnt vmcnt(0)" ::: "memory");
;         const unsigned old = __hip_atomic_fetch_add(bar, 1u, __ATOMIC_RELAXED, __HIP_MEMORY_SCOPE_AGENT);
.LBB0_1004:
	s_or_b64 exec, exec, s[42:43]
	s_waitcnt vmcnt(0) lgkmcnt(0)
	s_barrier
	s_mov_b64 s[42:43], exec
	v_readlane_b32 s2, v254, 32
	v_readlane_b32 s3, v254, 33
	s_and_b64 s[2:3], s[42:43], s[2:3]
	s_mov_b64 exec, s[2:3]
	s_cbranch_execz .LBB0_1013
	s_mov_b64 s[46:47], exec
	buffer_wbl2 sc1
	s_waitcnt vmcnt(0)
	s_waitcnt vmcnt(0)
	v_mbcnt_lo_u32_b32 v0, s46, 0
	v_mbcnt_hi_u32_b32 v0, s47, v0
	v_cmp_eq_u32_e32 vcc, 0, v0
	s_and_saveexec_b64 s[48:49], vcc
	s_cbranch_execz .LBB0_1007
	s_bcnt1_i32_b64 s2, s[46:47]
	v_mov_b32_e32 v1, s2
	v_readlane_b32 s2, v254, 35
	v_readlane_b32 s3, v254, 36
	s_nop 4
	s_cmpk_lg_u32 s45, 0x100
	s_cbranch_scc1 .Lhb_orig_9
	v_readlane_b32 vcc_lo, v253, 0
	s_and_b32 vcc_lo, vcc_lo, 7
	s_lshl_b32 vcc_lo, vcc_lo, 8
	s_addk_i32 vcc_lo, 0x1400
	v_mov_b32_e32 v0, vcc_lo
	v_mov_b32_e32 v1, 1
	global_atomic_add v1, v0, v1, s[2:3] sc0
	s_waitcnt vmcnt(0)
	v_readfirstlane_b32 vcc_lo, v1
	v_mov_b32_e32 v0, 0
	s_add_i32 vcc_lo, vcc_lo, 1
	s_and_b32 vcc_lo, vcc_lo, 31
	s_cmp_eq_u32 vcc_lo, 0
	s_cbranch_scc1 .Lhb_last_9
	v_mov_b32_e32 v1, 0x7fffff00
	s_branch .LBB0_1007
.Lhb_last_9:
	v_mov_b32_e32 v1, 32
	global_atomic_add v1, v0, v1, s[2:3] sc0
	s_waitcnt vmcnt(0)
	v_add_u32_e32 v1, 31, v1
	s_branch .LBB0_1007
.Lhb_orig_9:
	global_atomic_add v1, v161, v1, s[2:3] sc0

; __device__ __forceinline__ void grid_barrier(unsigned* bar, unsigned& epoch) {
;     asm volatile("s_waitcnt vmcnt(0) lgkmcnt(0)" ::: "memory");
;     __syncthreads();
;     epoch += 1;
;     if (threadIdx.x == 0) {
;         __builtin_amdgcn_fence(__ATOMIC_RELEASE, "agent");
;         asm volatile("s_waitcnt vmcnt(0)" ::: "memory");
;         const unsigned old = __hip_atomic_fetch_add(bar, 1u, __ATOMIC_RELAXED, __HIP_MEMORY_SCOPE_AGENT);
.LBB0_1045:
	s_waitcnt vmcnt(0) lgkmcnt(0)
	s_waitcnt vmcnt(0)
	s_barrier
	s_mov_b64 s[42:43], exec
	v_readlane_b32 s2, v254, 32
	v_readlane_b32 s3, v254, 33
	s_and_b64 s[2:3], s[42:43], s[2:3]
	s_mov_b64 exec, s[2:3]
	s_cbranch_execz .LBB0_1054
	s_mov_b64 s[46:47], exec
	buffer_wbl2 sc1
	s_waitcnt vmcnt(0)
	v_mbcnt_lo_u32_b32 v0, s46, 0
	v_mbcnt_hi_u32_b32 v0, s47, v0
	v_cmp_eq_u32_e32 vcc, 0, v0
	s_and_saveexec_b64 s[48:49], vcc
	s_cbranch_execz .LBB0_1048
	s_bcnt1_i32_b64 s2, s[46:47]
	v_mov_b32_e32 v1, s2
	v_readlane_b32 s2, v254, 35
	v_readlane_b32 s3, v254, 36
	s_nop 4
	s_cmpk_lg_u32 s45, 0x100
	s_cbranch_scc1 .Lhb_orig_10
	v_readlane_b32 vcc_lo, v253, 0
	s_and_b32 vcc_lo, vcc_lo, 7
	s_lshl_b32 vcc_lo, vcc_lo, 8
	s_addk_i32 vcc_lo, 0x1400
	v_mov_b32_e32 v0, vcc_lo
	v_mov_b32_e32 v1, 1
	global_atomic_add v1, v0, v1, s[2:3] sc0
	s_waitcnt vmcnt(0)
	v_readfirstlane_b32 vcc_lo, v1
	v_mov_b32_e32 v0, 0
	s_add_i32 vcc_lo, vcc_lo, 1
	s_and_b32 vcc_lo, vcc_lo, 31
	s_cmp_eq_u32 vcc_lo, 0
	s_cbranch_scc1 .Lhb_last_10
	v_mov_b32_e32 v1, 0x7fffff00
	s_branch .LBB0_1048

; __device__ __forceinline__ void grid_barrier(unsigned* bar, unsigned& epoch) {
;     asm volatile("s_waitcnt vmcnt(0) lgkmcnt(0)" ::: "memory");
;     __syncthreads();
;     epoch += 1;
;     if (threadIdx.x == 0) {
;         __builtin_amdgcn_fence(__ATOMIC_RELEASE, "agent");
;         asm volatile("s_waitcnt vmcnt(0)" ::: "memory");
;         const unsigned old = __hip_atomic_fetch_add(bar, 1u, __ATOMIC_RELAXED, __HIP_MEMORY_SCOPE_AGENT);
.LBB0_1113:
	s_waitcnt vmcnt(0) lgkmcnt(0)
	s_add_i32 s18, s82, 10
	s_waitcnt lgkmcnt(0)
	s_barrier
	s_mov_b64 s[4:5], exec
	v_readlane_b32 s2, v254, 32
	v_readlane_b32 s3, v254, 33
	s_and_b64 s[2:3], s[4:5], s[2:3]
	s_movk_i32 s52, 0x200
	s_mov_b64 exec, s[2:3]
	s_cbranch_execz .LBB0_1122
	s_mov_b64 s[6:7], exec
	buffer_wbl2 sc1
	s_waitcnt vmcnt(0)
	s_waitcnt vmcnt(0)
	v_mbcnt_lo_u32_b32 v0, s6, 0
	v_mbcnt_hi_u32_b32 v0, s7, v0
	v_cmp_eq_u32_e32 vcc, 0, v0
	s_and_saveexec_b64 s[42:43], vcc
	s_cbranch_execz .LBB0_1116
	s_bcnt1_i32_b64 s2, s[6:7]
	v_mov_b32_e32 v1, s2
	v_readlane_b32 s2, v254, 35
	v_readlane_b32 s3, v254, 36
	s_nop 4
	s_cmpk_lg_u32 s45, 0x100
	s_cbranch_scc1 .Lhb_orig_11
	v_readlane_b32 vcc_lo, v253, 0
	s_and_b32 vcc_lo, vcc_lo, 7
	s_lshl_b32 vcc_lo, vcc_lo, 8
	s_addk_i32 vcc_lo, 0x1400
	v_mov_b32_e32 v0, vcc_lo
	v_mov_b32_e32 v1, 1
	global_atomic_add v1, v0, v1, s[2:3] sc0
	s_waitcnt vmcnt(0)
	v_readfirstlane_b32 vcc_lo, v1
	v_mov_b32_e32 v0, 0
	s_add_i32 vcc_lo, vcc_lo, 1
	s_and_b32 vcc_lo, vcc_lo, 31
	s_cmp_eq_u32 vcc_lo, 0
	s_cbranch_scc1 .Lhb_last_11
	v_mov_b32_e32 v1, 0x7fffff00
	s_branch .LBB0_1116

; __device__ __forceinline__ void grid_barrier(unsigned* bar, unsigned& epoch) {
;     asm volatile("s_waitcnt vmcnt(0) lgkmcnt(0)" ::: "memory");
;     __syncthreads();
;     epoch += 1;
;     if (threadIdx.x == 0) {
;         __builtin_amdgcn_fence(__ATOMIC_RELEASE, "agent");
;         asm volatile("s_waitcnt vmcnt(0)" ::: "memory");
;         const unsigned old = __hip_atomic_fetch_add(bar, 1u, __ATOMIC_RELAXED, __HIP_MEMORY_SCOPE_AGENT);
.LBB0_1399:
	s_waitcnt vmcnt(0) lgkmcnt(0)
	s_add_i32 s18, s18, 1
	s_barrier
	s_mov_b64 s[2:3], exec
	v_readlane_b32 s4, v254, 32
	v_readlane_b32 s5, v254, 33
	s_and_b64 s[4:5], s[2:3], s[4:5]
	s_mov_b64 exec, s[4:5]
	s_cbranch_execz .LBB0_1398
	s_mov_b64 s[4:5], exec
	buffer_wbl2 sc1
	s_waitcnt vmcnt(0)
	s_waitcnt vmcnt(0)
	v_mbcnt_lo_u32_b32 v0, s4, 0
	v_mbcnt_hi_u32_b32 v0, s5, v0
	v_cmp_eq_u32_e32 vcc, 0, v0
	s_and_saveexec_b64 s[6:7], vcc
	s_cbranch_execz .LBB0_1402
	s_bcnt1_i32_b64 s4, s[4:5]
	v_mov_b32_e32 v1, s4
	v_readlane_b32 s4, v254, 35
	v_readlane_b32 s5, v254, 36
	s_nop 4
	s_cmpk_lg_u32 s45, 0x100
	s_cbranch_scc1 .Lhb_orig_12
	v_readlane_b32 vcc_lo, v253, 0
	s_and_b32 vcc_lo, vcc_lo, 7
	s_lshl_b32 vcc_lo, vcc_lo, 8
	s_addk_i32 vcc_lo, 0x1400
	v_mov_b32_e32 v0, vcc_lo
	v_mov_b32_e32 v1, 1
	global_atomic_add v1, v0, v1, s[4:5] sc0
	s_waitcnt vmcnt(0)
	v_readfirstlane_b32 vcc_lo, v1
	v_mov_b32_e32 v0, 0
	s_add_i32 vcc_lo, vcc_lo, 1
	s_and_b32 vcc_lo, vcc_lo, 31
	s_cmp_eq_u32 vcc_lo, 0
	s_cbranch_scc1 .Lhb_last_12
	v_mov_b32_e32 v1, 0x7fffff00
	s_branch .LBB0_1402

; __device__ __forceinline__ void grid_barrier(unsigned* bar, unsigned& epoch) {
;     asm volatile("s_waitcnt vmcnt(0) lgkmcnt(0)" ::: "memory");
;     __syncthreads();
;     epoch += 1;
;     if (threadIdx.x == 0) {
;         __builtin_amdgcn_fence(__ATOMIC_RELEASE, "agent");
;         asm volatile("s_waitcnt vmcnt(0)" ::: "memory");
;         const unsigned old = __hip_atomic_fetch_add(bar, 1u, __ATOMIC_RELAXED, __HIP_MEMORY_SCOPE_AGENT);
.LBB0_1410:
	s_mov_b64 s[4:5], exec
	buffer_wbl2 sc1
	s_waitcnt vmcnt(0)
	s_waitcnt vmcnt(0)
	v_mbcnt_lo_u32_b32 v0, s4, 0
	v_mbcnt_hi_u32_b32 v0, s5, v0
	v_cmp_eq_u32_e32 vcc, 0, v0
	s_and_saveexec_b64 s[6:7], vcc
	s_cbranch_execz .LBB0_1412
	s_bcnt1_i32_b64 s4, s[4:5]
	v_mov_b32_e32 v1, s4
	v_readlane_b32 s4, v254, 35
	v_readlane_b32 s5, v254, 36
	s_nop 4
	s_cmpk_lg_u32 s45, 0x100
	s_cbranch_scc1 .Lhb_orig_13
	v_readlane_b32 vcc_lo, v253, 0
	s_and_b32 vcc_lo, vcc_lo, 7
	s_lshl_b32 vcc_lo, vcc_lo, 8
	s_addk_i32 vcc_lo, 0x1400
	v_mov_b32_e32 v0, vcc_lo
	v_mov_b32_e32 v1, 1
	global_atomic_add v1, v0, v1, s[4:5] sc0
	s_waitcnt vmcnt(0)
	v_readfirstlane_b32 vcc_lo, v1
	v_mov_b32_e32 v0, 0
	s_add_i32 vcc_lo, vcc_lo, 1
	s_and_b32 vcc_lo, vcc_lo, 31
	s_cmp_eq_u32 vcc_lo, 0
	s_cbranch_scc1 .Lhb_last_13
	v_mov_b32_e32 v1, 0x7fffff00
	s_branch .LBB0_1412
